# inproj K-loop operand loads bypass the vector L1 (sc1): no L1 reuse exists within a tile
# speedup vs baseline: 1.0196x; 1.0196x over previous
;   __device__ __forceinline__ const float* x() const { return (const float*)(const __attribute__((address_space(1))) float*)kp[0]; }
; template <class LA, class LB, class EP>
; __device__ __forceinline__ void gemm_tile_big(int K, LA loadA, LB loadB, EP epi, char* smem) {
;   half_t* sA = (half_t*)smem;
;   half_t* sB = sA + 256 * 72;
;   int tid = threadIdx.x;
;   asm volatile("" : "+v"(tid));
;   const int lane = tid & 63, wid = tid >> 6;
;   const int wm = wid >> 1, wn = wid & 1;
;   f32x16 acc[4][2];
; #pragma unroll
;   for (int i = 0; i < 4; ++i)
; #pragma unroll
;     for (int j = 0; j < 2; ++j)
; #pragma unroll
;       for (int r = 0; r < 16; ++r) acc[i][j][r] = 0.f;
;   const int lr = tid >> 3, lc = (tid & 7) * 8;
;   uint4 ra[8], rb[4];
; #pragma unroll
;   for (int i = 0; i < 8; ++i) ra[i] = loadA(lr + 32 * i, lc);
; #pragma unroll
;   for (int i = 0; i < 4; ++i) rb[i] = loadB(lr + 32 * i, lc);
.LBB0_285:
	s_lshl_b32 s2, s42, 2
	s_and_b32 s2, s2, 60
	s_and_b32 s15, s43, 3
	s_or_b32 s14, s2, s15
	v_mov_b32_e32 v194, v224
	s_lshl_b32 s30, s14, 19
	s_lshl_b64 s[2:3], s[18:19], 11
	s_add_u32 s30, s8, s30
	v_ashrrev_i32_e32 v2, 3, v194
	v_lshlrev_b32_e32 v0, 3, v194
	v_and_b32_e32 v20, 56, v0
	v_ashrrev_i32_e32 v3, 31, v2
	s_addc_u32 s31, s44, 0
	v_lshlrev_b32_e32 v0, 1, v20
	v_lshlrev_b64 v[6:7], 11, v[2:3]
	v_lshl_add_u64 v[4:5], s[30:31], 0, v[0:1]
	v_lshl_add_u64 v[10:11], v[6:7], 0, s[20:21]
	v_lshl_add_u64 v[8:9], v[4:5], 0, v[6:7]
	v_lshl_add_u64 v[12:13], v[4:5], 0, v[10:11]
	v_lshl_add_u64 v[12:13], v[6:7], 0, s[80:81]
	v_lshl_add_u64 v[14:15], v[4:5], 0, v[12:13]
	v_lshl_add_u64 v[16:17], v[6:7], 0, s[82:83]
	v_lshl_add_u64 v[18:19], v[4:5], 0, v[16:17]
	v_add_u32_e32 v14, 0x80, v2
	v_ashrrev_i32_e32 v15, 31, v14
	v_lshlrev_b64 v[18:19], 11, v[14:15]
	v_lshl_add_u64 v[4:5], v[4:5], 0, v[18:19]
	v_add_co_u32_e32 v18, vcc, s61, v8
	s_add_u32 s42, s45, s2
	s_nop 0
	v_addc_co_u32_e32 v19, vcc, 0, v9, vcc
	v_add_co_u32_e32 v4, vcc, s64, v8
	s_addc_u32 s43, s46, s3
	s_nop 0
	v_addc_co_u32_e32 v5, vcc, 0, v9, vcc
	v_add_co_u32_e32 v8, vcc, s65, v8
	v_and_b32_e32 v3, 0xfffff9f, v194
	s_nop 0
	v_addc_co_u32_e32 v9, vcc, 0, v9, vcc
	v_lshl_add_u64 v[4:5], s[42:43], 0, v[0:1]
	v_lshl_add_u64 v[8:9], v[4:5], 0, v[6:7]
	v_lshl_add_u64 v[10:11], v[4:5], 0, v[10:11]
	v_lshl_add_u64 v[8:9], v[4:5], 0, v[12:13]
	v_lshl_add_u64 v[4:5], v[4:5], 0, v[16:17]
	v_lshrrev_b32_e32 v4, 1, v194
	v_and_b32_e32 v4, 16, v4
	v_mul_lo_u32 v2, v2, s37
	v_bfe_u32 v247, v194, 6, 1
	v_and_b32_e32 v195, 31, v194
	v_mad_u64_u32 v[178:179], s[30:31], v3, s36, v[4:5]
	v_add_lshl_u32 v196, v2, v20, 1
	v_lshl_add_u64 v[2:3], v[6:7], 0, s[2:3]
	s_add_i32 s2, s52, s53
	v_lshl_or_b32 v249, v247, 6, v195
	v_mad_u64_u32 v[188:189], s[30:31], v14, s36, v[0:1]
	v_or_b32_e32 v0, 0x60, v194
	s_lshl_b32 s2, s2, 19
	v_mad_u64_u32 v[180:181], s[30:31], v0, s36, v[4:5]
	v_mad_u32_u24 v179, v249, s36, v4
	v_lshlrev_b32_e32 v4, 4, v194
	s_and_b32 s2, s2, 0x1e00000
	s_lshl_b32 s3, s15, 19
	v_and_b32_e32 v4, 0x70, v4
	s_or_b32 s2, s2, s3
	v_or_b32_e32 v2, v2, v4
	s_add_u32 s2, s0, s2
	v_lshl_add_u64 v[190:191], s[0:1], 0, v[2:3]
	v_or_b32_e32 v6, v6, v4
	s_addc_u32 s3, s1, 0
	v_mov_b32_e32 v2, 0
	v_add_u32_e32 v198, 0x1200, v188
	v_add_u32_e32 v197, 0x2400, v188
	v_add_u32_e32 v189, 0x3600, v188
	v_add_u32_e32 v0, 0x1200, v179
	v_lshl_add_u64 v[192:193], s[2:3], 0, v[6:7]
	v_mov_b32_e32 v3, v2
	v_mov_b32_e32 v4, v2
	v_mov_b32_e32 v5, v2
	v_mov_b32_e32 v6, v2
	v_mov_b32_e32 v7, v2
	v_mov_b32_e32 v8, v2
	v_mov_b32_e32 v9, v2
	v_mov_b32_e32 v10, v2
	v_mov_b32_e32 v11, v2
	v_mov_b32_e32 v12, v2
	v_mov_b32_e32 v13, v2
	v_mov_b32_e32 v14, v2
	v_mov_b32_e32 v15, v2
	v_mov_b32_e32 v16, v2
	v_mov_b32_e32 v17, v2
	v_mov_b32_e32 v18, v2
	v_mov_b32_e32 v19, v2
	v_mov_b32_e32 v20, v2
	v_mov_b32_e32 v21, v2
	v_mov_b32_e32 v22, v2
	v_mov_b32_e32 v23, v2
	v_mov_b32_e32 v24, v2
	v_mov_b32_e32 v25, v2
	v_mov_b32_e32 v26, v2
	v_mov_b32_e32 v27, v2
	v_mov_b32_e32 v28, v2
	v_mov_b32_e32 v29, v2
	v_mov_b32_e32 v30, v2
	v_mov_b32_e32 v31, v2
	v_mov_b32_e32 v32, v2
	v_mov_b32_e32 v33, v2
	v_mov_b32_e32 v34, v2
	v_mov_b32_e32 v35, v2
	v_mov_b32_e32 v36, v2
	v_mov_b32_e32 v37, v2
	v_mov_b32_e32 v38, v2
	v_mov_b32_e32 v39, v2
	v_mov_b32_e32 v40, v2
	v_mov_b32_e32 v41, v2
	v_mov_b32_e32 v42, v2
	v_mov_b32_e32 v43, v2
	v_mov_b32_e32 v44, v2
	v_mov_b32_e32 v45, v2
	v_mov_b32_e32 v46, v2
	v_mov_b32_e32 v47, v2
	v_mov_b32_e32 v48, v2
	v_mov_b32_e32 v49, v2
	v_mov_b32_e32 v50, v2
	v_mov_b32_e32 v51, v2
	v_mov_b32_e32 v52, v2
	v_mov_b32_e32 v53, v2
	v_mov_b32_e32 v54, v2
	v_mov_b32_e32 v55, v2
	v_mov_b32_e32 v56, v2
	v_mov_b32_e32 v57, v2
	v_mov_b32_e32 v58, v2
	v_mov_b32_e32 v59, v2
	v_mov_b32_e32 v60, v2
	v_mov_b32_e32 v61, v2
	v_mov_b32_e32 v62, v2
	v_mov_b32_e32 v63, v2
	v_mov_b32_e32 v64, v2
	v_mov_b32_e32 v65, v2
	v_mov_b32_e32 v66, v2
	v_mov_b32_e32 v67, v2
	v_mov_b32_e32 v68, v2
	v_mov_b32_e32 v69, v2
	v_mov_b32_e32 v70, v2
	v_mov_b32_e32 v71, v2
	v_mov_b32_e32 v72, v2
	v_mov_b32_e32 v73, v2
	v_mov_b32_e32 v74, v2
	v_mov_b32_e32 v75, v2
	v_mov_b32_e32 v76, v2
	v_mov_b32_e32 v77, v2
	v_mov_b32_e32 v78, v2
	v_mov_b32_e32 v79, v2
	v_mov_b32_e32 v80, v2
	v_mov_b32_e32 v81, v2
	v_mov_b32_e32 v82, v2
	v_mov_b32_e32 v83, v2
	v_mov_b32_e32 v84, v2
	v_mov_b32_e32 v85, v2
	v_mov_b32_e32 v86, v2
	v_mov_b32_e32 v87, v2
	v_mov_b32_e32 v88, v2
	v_mov_b32_e32 v89, v2
	v_mov_b32_e32 v90, v2
	v_mov_b32_e32 v91, v2
	v_mov_b32_e32 v92, v2
	v_mov_b32_e32 v93, v2
	v_mov_b32_e32 v94, v2
	v_mov_b32_e32 v95, v2
	v_mov_b32_e32 v96, v2
	v_mov_b32_e32 v97, v2
	v_mov_b32_e32 v98, v2
	v_mov_b32_e32 v99, v2
	v_mov_b32_e32 v100, v2
	v_mov_b32_e32 v101, v2
	v_mov_b32_e32 v102, v2
	v_mov_b32_e32 v103, v2
	v_mov_b32_e32 v104, v2
	v_mov_b32_e32 v105, v2
	v_mov_b32_e32 v106, v2
	v_mov_b32_e32 v107, v2
	v_mov_b32_e32 v108, v2
	v_mov_b32_e32 v109, v2
	v_mov_b32_e32 v110, v2
	v_mov_b32_e32 v111, v2
	v_mov_b32_e32 v112, v2
	v_mov_b32_e32 v113, v2
	v_mov_b32_e32 v114, v2
	v_mov_b32_e32 v115, v2
	v_mov_b32_e32 v116, v2
	v_mov_b32_e32 v117, v2
	v_mov_b32_e32 v118, v2
	v_mov_b32_e32 v119, v2
	v_mov_b32_e32 v120, v2
	v_mov_b32_e32 v121, v2
	v_mov_b32_e32 v122, v2
	v_mov_b32_e32 v123, v2
	v_mov_b32_e32 v124, v2
	v_mov_b32_e32 v125, v2
	v_mov_b32_e32 v126, v2
	v_mov_b32_e32 v127, v2
	v_mov_b32_e32 v128, v2
	v_mov_b32_e32 v129, v2
	v_lshrrev_b32_e32 v208, 2, v194
	v_and_b32_e32 v209, 3, v194
	v_lshlrev_b32_e32 v210, 11, v208
	v_mul_u32_u24_e32 v196, 0x50, v208
	v_lshl_add_u32 v196, v209, 4, v196
	v_lshlrev_b32_e32 v208, 4, v194
	v_add_u32_e32 v209, 0x1000, v208
	v_add_u32_e32 v210, 0x2000, v208
	v_add_u32_e32 v211, 0x3000, v208
	v_lshrrev_b32_e32 v178, 7, v194
	v_and_b32_e32 v179, 31, v194
	v_lshl_or_b32 v178, v178, 7, v179
	v_mul_u32_u24_e32 v178, 0x50, v178
	v_bfe_u32 v212, v194, 5, 1
	v_lshl_add_u32 v178, v212, 4, v178
	v_bfe_u32 v213, v194, 6, 1
	v_lshl_or_b32 v179, v213, 6, v179
	v_mul_u32_u24_e32 v179, 0x50, v179
	v_lshl_add_u32 v179, v212, 4, v179
	s_lshl_b32 s38, s14, 14
	s_add_u32 s38, s8, s38
	s_addc_u32 s39, s44, 0
	s_lshl_b64 s[2:3], s[18:19], 6
	s_add_u32 s2, s45, s2
	s_addc_u32 s3, s46, s3
	global_load_dwordx4 v[130:133], v208, s[38:39] sc1
	global_load_dwordx4 v[134:137], v209, s[38:39] sc1
	global_load_dwordx4 v[138:141], v210, s[38:39] sc1
	global_load_dwordx4 v[142:145], v211, s[38:39] sc1
	global_load_dwordx4 v[146:149], v208, s[2:3] sc1
	global_load_dwordx4 v[150:153], v209, s[2:3] sc1
	s_add_u32 s38, s38, 0x100000
	s_addc_u32 s39, s39, 0
	s_add_u32 s2, s2, 0x74000
	s_addc_u32 s3, s3, 0
	global_load_dwordx4 v[154:157], v208, s[38:39] sc1
	global_load_dwordx4 v[158:161], v209, s[38:39] sc1
	global_load_dwordx4 v[162:165], v210, s[38:39] sc1
	global_load_dwordx4 v[166:169], v211, s[38:39] sc1
	global_load_dwordx4 v[170:173], v208, s[2:3] sc1
	global_load_dwordx4 v[174:177], v209, s[2:3] sc1
	s_add_u32 s38, s38, 0x100000
	s_addc_u32 s39, s39, 0
	s_add_u32 s2, s2, 0x74000
	s_addc_u32 s3, s3, 0
	s_barrier
; template <class LA, class LB, class EP>
; __device__ __forceinline__ void gemm_tile_big(int K, LA loadA, LB loadB, EP epi, char* smem) {
;     ...
;   for (int kt = 0; kt < nk; ++kt) {
;     __syncthreads();
; #pragma unroll
;     for (int i = 0; i < 8; ++i) *(uint4*)&sA[(lr + 32 * i) * 72 + lc] = ra[i];
; #pragma unroll
;     for (int i = 0; i < 4; ++i) *(uint4*)&sB[(lr + 32 * i) * 72 + lc] = rb[i];
;     __syncthreads();
;     if (kt + 1 < nk) {
;       const int kk = (kt + 1) * 64 + lc;
; #pragma unroll
;       for (int i = 0; i < 8; ++i) ra[i] = loadA(lr + 32 * i, kk);
; #pragma unroll
;       for (int i = 0; i < 4; ++i) rb[i] = loadB(lr + 32 * i, kk);
;     }
; #pragma unroll
;     for (int s = 0; s < 4; ++s) {
;       h8 af[4], bf[2];
; #pragma unroll
;       for (int mi = 0; mi < 4; ++mi)
;         af[mi] = *(const h8*)&sA[(wm * 128 + mi * 32 + (lane & 31)) * 72 + s * 16 + (lane >> 5) * 8];
; #pragma unroll
;       for (int ni = 0; ni < 2; ++ni)
;         bf[ni] = *(const h8*)&sB[(wn * 64 + ni * 32 + (lane & 31)) * 72 + s * 16 + (lane >> 5) * 8];
; #pragma unroll
;       for (int mi = 0; mi < 4; ++mi)
; #pragma unroll
;         for (int ni = 0; ni < 2; ++ni)
;           acc[mi][ni] = __builtin_amdgcn_mfma_f32_32x32x16_f16(af[mi], bf[ni], acc[mi][ni], 0, 0, 0);
;     }
	s_waitcnt vmcnt(11)
	ds_write_b128 v196, v[130:133]
	s_waitcnt vmcnt(10)
	ds_write_b128 v196, v[134:137] offset:5120
	s_waitcnt vmcnt(9)
	ds_write_b128 v196, v[138:141] offset:10240
	s_waitcnt vmcnt(8)
	ds_write_b128 v196, v[142:145] offset:15360
	s_waitcnt vmcnt(7)
	ds_write_b128 v196, v[146:149] offset:20480
	s_waitcnt vmcnt(6)
	ds_write_b128 v196, v[150:153] offset:25600
	s_waitcnt lgkmcnt(0)
	s_barrier
	s_mov_b32 s30, 0
.Lgp1_loop:
	ds_read_b128 v[238:241], v179 offset:20480
	ds_read_b128 v[242:245], v179 offset:23040
	ds_read_b128 v[200:203], v178
	ds_read_b128 v[204:207], v178 offset:2560
	ds_read_b128 v[214:217], v178 offset:5120
	ds_read_b128 v[218:221], v178 offset:7680
	global_load_dwordx4 v[130:133], v208, s[38:39] sc1
	global_load_dwordx4 v[134:137], v209, s[38:39] sc1
	global_load_dwordx4 v[138:141], v210, s[38:39] sc1
	global_load_dwordx4 v[142:145], v211, s[38:39] sc1
	global_load_dwordx4 v[146:149], v208, s[2:3] sc1
	global_load_dwordx4 v[150:153], v209, s[2:3] sc1
	s_add_u32 s38, s38, 0x100000
	s_addc_u32 s39, s39, 0
	s_add_u32 s2, s2, 0x74000
	s_addc_u32 s3, s3, 0
	ds_read_b128 v[226:229], v179 offset:20512
	ds_read_b128 v[230:233], v179 offset:23072
	s_waitcnt lgkmcnt(5)
	v_mfma_f32_32x32x16_f16 v[114:129], v[200:203], v[238:241], v[114:129]
	v_mfma_f32_32x32x16_f16 v[98:113], v[200:203], v[242:245], v[98:113]
	ds_read_b128 v[200:203], v178 offset:32
	s_waitcnt lgkmcnt(5)
	v_mfma_f32_32x32x16_f16 v[82:97], v[204:207], v[238:241], v[82:97]
	v_mfma_f32_32x32x16_f16 v[66:81], v[204:207], v[242:245], v[66:81]
	ds_read_b128 v[204:207], v178 offset:2592
	s_waitcnt vmcnt(11)
	ds_write_b128 v196, v[154:157] offset:30720
	s_waitcnt lgkmcnt(6)
	v_mfma_f32_32x32x16_f16 v[50:65], v[214:217], v[238:241], v[50:65]
	v_mfma_f32_32x32x16_f16 v[34:49], v[214:217], v[242:245], v[34:49]
	ds_read_b128 v[214:217], v178 offset:5152
	s_waitcnt vmcnt(10)
	ds_write_b128 v196, v[158:161] offset:35840
	s_waitcnt lgkmcnt(7)
	v_mfma_f32_32x32x16_f16 v[18:33], v[218:221], v[238:241], v[18:33]
	v_mfma_f32_32x32x16_f16 v[2:17], v[218:221], v[242:245], v[2:17]
	ds_read_b128 v[218:221], v178 offset:7712
	s_waitcnt vmcnt(9)
	ds_write_b128 v196, v[162:165] offset:40960
	s_waitcnt lgkmcnt(6)
	v_mfma_f32_32x32x16_f16 v[114:129], v[200:203], v[226:229], v[114:129]
	v_mfma_f32_32x32x16_f16 v[98:113], v[200:203], v[230:233], v[98:113]
	s_waitcnt vmcnt(8)
	ds_write_b128 v196, v[166:169] offset:46080
	s_waitcnt lgkmcnt(6)
	v_mfma_f32_32x32x16_f16 v[82:97], v[204:207], v[226:229], v[82:97]
	v_mfma_f32_32x32x16_f16 v[66:81], v[204:207], v[230:233], v[66:81]
	s_waitcnt vmcnt(7)
	ds_write_b128 v196, v[170:173] offset:51200
	s_waitcnt lgkmcnt(5)
	v_mfma_f32_32x32x16_f16 v[50:65], v[214:217], v[226:229], v[50:65]
	v_mfma_f32_32x32x16_f16 v[34:49], v[214:217], v[230:233], v[34:49]
	s_waitcnt vmcnt(6)
	ds_write_b128 v196, v[174:177] offset:56320
	s_waitcnt lgkmcnt(4)
	v_mfma_f32_32x32x16_f16 v[18:33], v[218:221], v[226:229], v[18:33]
	v_mfma_f32_32x32x16_f16 v[2:17], v[218:221], v[230:233], v[2:17]
	s_waitcnt lgkmcnt(0)
	s_barrier
	ds_read_b128 v[238:241], v179 offset:51200
	ds_read_b128 v[242:245], v179 offset:53760
	ds_read_b128 v[200:203], v178 offset:30720
	ds_read_b128 v[204:207], v178 offset:33280
	ds_read_b128 v[214:217], v178 offset:35840
	ds_read_b128 v[218:221], v178 offset:38400
	global_load_dwordx4 v[154:157], v208, s[38:39] sc1
	global_load_dwordx4 v[158:161], v209, s[38:39] sc1
	global_load_dwordx4 v[162:165], v210, s[38:39] sc1
	global_load_dwordx4 v[166:169], v211, s[38:39] sc1
	global_load_dwordx4 v[170:173], v208, s[2:3] sc1
	global_load_dwordx4 v[174:177], v209, s[2:3] sc1
	s_add_u32 s38, s38, 0x100000
	s_addc_u32 s39, s39, 0
	s_add_u32 s2, s2, 0x74000
	s_addc_u32 s3, s3, 0
	ds_read_b128 v[226:229], v179 offset:51232
	ds_read_b128 v[230:233], v179 offset:53792
	s_waitcnt lgkmcnt(5)
	v_mfma_f32_32x32x16_f16 v[114:129], v[200:203], v[238:241], v[114:129]
	v_mfma_f32_32x32x16_f16 v[98:113], v[200:203], v[242:245], v[98:113]
	ds_read_b128 v[200:203], v178 offset:30752
	s_waitcnt lgkmcnt(5)
	v_mfma_f32_32x32x16_f16 v[82:97], v[204:207], v[238:241], v[82:97]
	v_mfma_f32_32x32x16_f16 v[66:81], v[204:207], v[242:245], v[66:81]
	ds_read_b128 v[204:207], v178 offset:33312
	s_waitcnt vmcnt(11)
	ds_write_b128 v196, v[130:133]
	s_waitcnt lgkmcnt(6)
	v_mfma_f32_32x32x16_f16 v[50:65], v[214:217], v[238:241], v[50:65]
	v_mfma_f32_32x32x16_f16 v[34:49], v[214:217], v[242:245], v[34:49]
	ds_read_b128 v[214:217], v178 offset:35872
	s_waitcnt vmcnt(10)
	ds_write_b128 v196, v[134:137] offset:5120
	s_waitcnt lgkmcnt(7)
	v_mfma_f32_32x32x16_f16 v[18:33], v[218:221], v[238:241], v[18:33]
	v_mfma_f32_32x32x16_f16 v[2:17], v[218:221], v[242:245], v[2:17]
	ds_read_b128 v[218:221], v178 offset:38432
	s_waitcnt vmcnt(9)
	ds_write_b128 v196, v[138:141] offset:10240
	s_waitcnt lgkmcnt(6)
	v_mfma_f32_32x32x16_f16 v[114:129], v[200:203], v[226:229], v[114:129]
	v_mfma_f32_32x32x16_f16 v[98:113], v[200:203], v[230:233], v[98:113]
	s_waitcnt vmcnt(8)
	ds_write_b128 v196, v[142:145] offset:15360
	s_waitcnt lgkmcnt(6)
	v_mfma_f32_32x32x16_f16 v[82:97], v[204:207], v[226:229], v[82:97]
	v_mfma_f32_32x32x16_f16 v[66:81], v[204:207], v[230:233], v[66:81]
	s_waitcnt vmcnt(7)
	ds_write_b128 v196, v[146:149] offset:20480
	s_waitcnt lgkmcnt(5)
	v_mfma_f32_32x32x16_f16 v[50:65], v[214:217], v[226:229], v[50:65]
	v_mfma_f32_32x32x16_f16 v[34:49], v[214:217], v[230:233], v[34:49]
	s_waitcnt vmcnt(6)
	ds_write_b128 v196, v[150:153] offset:25600
	s_waitcnt lgkmcnt(4)
	v_mfma_f32_32x32x16_f16 v[18:33], v[218:221], v[226:229], v[18:33]
	v_mfma_f32_32x32x16_f16 v[2:17], v[218:221], v[230:233], v[2:17]
	s_waitcnt lgkmcnt(0)
	s_barrier
; template <class LA, class LB, class EP>
; __device__ __forceinline__ void gemm_tile_big(int K, LA loadA, LB loadB, EP epi, char* smem) {
;     ...
; #pragma unroll
;     for (int s = 0; s < 4; ++s) {
;       h8 af[4], bf[2];
; #pragma unroll
;       for (int mi = 0; mi < 4; ++mi)
;         af[mi] = *(const h8*)&sA[(wm * 128 + mi * 32 + (lane & 31)) * 72 + s * 16 + (lane >> 5) * 8];
; #pragma unroll
;       for (int ni = 0; ni < 2; ++ni)
;         bf[ni] = *(const h8*)&sB[(wn * 64 + ni * 32 + (lane & 31)) * 72 + s * 16 + (lane >> 5) * 8];
; #pragma unroll
;       for (int mi = 0; mi < 4; ++mi)
; #pragma unroll
;         for (int ni = 0; ni < 2; ++ni)
;           acc[mi][ni] = __builtin_amdgcn_mfma_f32_32x32x16_f16(af[mi], bf[ni], acc[mi][ni], 0, 0, 0);
;     }
;   }
; #pragma unroll
;   for (int mi = 0; mi < 4; ++mi)
; #pragma unroll
;     for (int ni = 0; ni < 2; ++ni)
; #pragma unroll
;       for (int r = 0; r < 16; ++r) {
;         const int row = wm * 128 + mi * 32 + (r & 3) + 8 * (r >> 2) + 4 * (lane >> 5);
;         const int col = wn * 64 + ni * 32 + (lane & 31);
;         epi(mi, ni, r, row, col, acc[mi][ni][r]);
; __device__ __forceinline__ void phase_inproj(const KP& p, int l, char* smem, int* q, int xcc) {
;     ...
;         [&](int mi, int ni, int r, int row, int col, float v) {
;           const half_t hv = (half_t)(v + bv[ni]);
	s_add_i32 s30, s30, 1
	s_cmp_lt_u32 s30, 15
	s_cbranch_scc1 .Lgp1_loop
	ds_read_b128 v[238:241], v179 offset:20480
	ds_read_b128 v[242:245], v179 offset:23040
	ds_read_b128 v[200:203], v178
	ds_read_b128 v[204:207], v178 offset:2560
	ds_read_b128 v[214:217], v178 offset:5120
	ds_read_b128 v[218:221], v178 offset:7680
	ds_read_b128 v[226:229], v179 offset:20512
	ds_read_b128 v[230:233], v179 offset:23072
	s_waitcnt lgkmcnt(5)
	v_mfma_f32_32x32x16_f16 v[114:129], v[200:203], v[238:241], v[114:129]
	v_mfma_f32_32x32x16_f16 v[98:113], v[200:203], v[242:245], v[98:113]
	ds_read_b128 v[200:203], v178 offset:32
	s_waitcnt lgkmcnt(5)
	v_mfma_f32_32x32x16_f16 v[82:97], v[204:207], v[238:241], v[82:97]
	v_mfma_f32_32x32x16_f16 v[66:81], v[204:207], v[242:245], v[66:81]
	ds_read_b128 v[204:207], v178 offset:2592
	s_waitcnt vmcnt(5)
	ds_write_b128 v196, v[154:157] offset:30720
	s_waitcnt lgkmcnt(6)
	v_mfma_f32_32x32x16_f16 v[50:65], v[214:217], v[238:241], v[50:65]
	v_mfma_f32_32x32x16_f16 v[34:49], v[214:217], v[242:245], v[34:49]
	ds_read_b128 v[214:217], v178 offset:5152
	s_waitcnt vmcnt(4)
	ds_write_b128 v196, v[158:161] offset:35840
	s_waitcnt lgkmcnt(7)
	v_mfma_f32_32x32x16_f16 v[18:33], v[218:221], v[238:241], v[18:33]
	v_mfma_f32_32x32x16_f16 v[2:17], v[218:221], v[242:245], v[2:17]
	ds_read_b128 v[218:221], v178 offset:7712
	s_waitcnt vmcnt(3)
	ds_write_b128 v196, v[162:165] offset:40960
	s_waitcnt lgkmcnt(6)
	v_mfma_f32_32x32x16_f16 v[114:129], v[200:203], v[226:229], v[114:129]
	v_mfma_f32_32x32x16_f16 v[98:113], v[200:203], v[230:233], v[98:113]
	s_waitcnt vmcnt(2)
	ds_write_b128 v196, v[166:169] offset:46080
	s_waitcnt lgkmcnt(6)
	v_mfma_f32_32x32x16_f16 v[82:97], v[204:207], v[226:229], v[82:97]
	v_mfma_f32_32x32x16_f16 v[66:81], v[204:207], v[230:233], v[66:81]
	s_waitcnt vmcnt(1)
	ds_write_b128 v196, v[170:173] offset:51200
	s_waitcnt lgkmcnt(5)
	v_mfma_f32_32x32x16_f16 v[50:65], v[214:217], v[226:229], v[50:65]
	v_mfma_f32_32x32x16_f16 v[34:49], v[214:217], v[230:233], v[34:49]
	s_waitcnt vmcnt(0)
	ds_write_b128 v196, v[174:177] offset:56320
	s_waitcnt lgkmcnt(4)
	v_mfma_f32_32x32x16_f16 v[18:33], v[218:221], v[226:229], v[18:33]
	v_mfma_f32_32x32x16_f16 v[2:17], v[218:221], v[230:233], v[2:17]
	s_waitcnt lgkmcnt(0)
	s_barrier
	ds_read_b128 v[238:241], v179 offset:51200
	ds_read_b128 v[242:245], v179 offset:53760
	ds_read_b128 v[200:203], v178 offset:30720
	ds_read_b128 v[204:207], v178 offset:33280
	ds_read_b128 v[214:217], v178 offset:35840
	ds_read_b128 v[218:221], v178 offset:38400
	ds_read_b128 v[226:229], v179 offset:51232
	ds_read_b128 v[230:233], v179 offset:53792
	s_waitcnt lgkmcnt(5)
	v_mfma_f32_32x32x16_f16 v[114:129], v[200:203], v[238:241], v[114:129]
	v_mfma_f32_32x32x16_f16 v[98:113], v[200:203], v[242:245], v[98:113]
	ds_read_b128 v[200:203], v178 offset:30752
	s_waitcnt lgkmcnt(5)
	v_mfma_f32_32x32x16_f16 v[82:97], v[204:207], v[238:241], v[82:97]
	v_mfma_f32_32x32x16_f16 v[66:81], v[204:207], v[242:245], v[66:81]
	ds_read_b128 v[204:207], v178 offset:33312
	s_waitcnt lgkmcnt(5)
	v_mfma_f32_32x32x16_f16 v[50:65], v[214:217], v[238:241], v[50:65]
	v_mfma_f32_32x32x16_f16 v[34:49], v[214:217], v[242:245], v[34:49]
	ds_read_b128 v[214:217], v178 offset:35872
	s_waitcnt lgkmcnt(5)
	v_mfma_f32_32x32x16_f16 v[18:33], v[218:221], v[238:241], v[18:33]
	v_mfma_f32_32x32x16_f16 v[2:17], v[218:221], v[242:245], v[2:17]
	ds_read_b128 v[218:221], v178 offset:38432
	s_waitcnt lgkmcnt(3)
	v_mfma_f32_32x32x16_f16 v[114:129], v[200:203], v[226:229], v[114:129]
	v_mfma_f32_32x32x16_f16 v[98:113], v[200:203], v[230:233], v[98:113]
	s_waitcnt lgkmcnt(2)
	v_mfma_f32_32x32x16_f16 v[82:97], v[204:207], v[226:229], v[82:97]
	v_mfma_f32_32x32x16_f16 v[66:81], v[204:207], v[230:233], v[66:81]
	s_waitcnt lgkmcnt(1)
	v_mfma_f32_32x32x16_f16 v[50:65], v[214:217], v[226:229], v[50:65]
	v_mfma_f32_32x32x16_f16 v[34:49], v[214:217], v[230:233], v[34:49]
	s_waitcnt lgkmcnt(0)
	v_mfma_f32_32x32x16_f16 v[18:33], v[218:221], v[226:229], v[18:33]
	v_mfma_f32_32x32x16_f16 v[2:17], v[218:221], v[230:233], v[2:17]
	s_waitcnt lgkmcnt(0)
	v_mov_b32_e32 v226, 1
	v_mov_b32_e32 v227, 0x11fe0
	v_mov_b32_e32 v228, 0x11fe4
	v_mov_b32_e32 v229, 0x100
	v_mov_b32_e32 v230, 2
	v_mov_b32_e32 v231, 0x3727c5ac
	v_mov_b32_e32 v232, 0x11fa0
	v_mov_b32_e32 v233, 0x80000
	v_mov_b32_e32 v238, 0x4000
	v_mov_b32_e32 v239, 0x4400
	v_mov_b32_e32 v240, 0x4800
	v_mov_b32_e32 v241, 0x4c00
	v_mov_b32_e32 v242, 0xf149f2ca
	v_mov_b32_e32 v243, 0x200
	v_mov_b32_e32 v244, 0x400
	v_mov_b32_e32 v245, 0x600
	s_nop 15
	s_lshl_b32 s14, s14, 8
	s_lshl_b64 s[2:3], s[18:19], 1
	s_add_u32 s18, s47, s2
	s_addc_u32 s19, s48, s3
	s_mul_i32 s2, s14, 0x3a00
	s_add_u32 s18, s18, s2
	s_addc_u32 s19, s19, 0
	v_lshrrev_b32_e32 v130, 7, v224
	v_lshlrev_b32_e32 v130, 5, v130
	v_bfe_u32 v131, v224, 5, 1
	v_add_u32_e32 v130, v130, v131
	v_mul_u32_u24_e32 v132, 0xe800, v130
	v_bfe_u32 v131, v224, 6, 1
	v_and_b32_e32 v133, 31, v224
	v_lshl_or_b32 v134, v131, 6, v133
	v_lshl_add_u32 v132, v134, 1, v132
	v_add_f32_e32 v114, v246, v114
	v_cvt_f16_f32_e32 v114, v114
	v_add_f32_e32 v115, v246, v115
	v_cvt_f16_f32_e32 v115, v115
	v_add_f32_e32 v116, v246, v116
	v_cvt_f16_f32_e32 v116, v116
	v_add_f32_e32 v117, v246, v117
	v_cvt_f16_f32_e32 v117, v117
	v_add_f32_e32 v118, v246, v118
	v_cvt_f16_f32_e32 v118, v118
	v_add_f32_e32 v119, v246, v119
	v_cvt_f16_f32_e32 v119, v119
	v_add_f32_e32 v120, v246, v120
	v_cvt_f16_f32_e32 v120, v120
	v_add_f32_e32 v121, v246, v121
	v_cvt_f16_f32_e32 v121, v121
	v_add_f32_e32 v122, v246, v122
	v_cvt_f16_f32_e32 v122, v122
	v_add_f32_e32 v123, v246, v123
	v_cvt_f16_f32_e32 v123, v123
;   __device__ __forceinline__ half_t* u() const { return (half_t*)(ws() + OFF_u); }
; __device__ __forceinline__ void phase_inproj(const KP& p, int l, char* smem, int* q, int xcc) {
;     ...
;         [&](int mi, int ni, int r, int row, int col, float v) {
;           const half_t hv = (half_t)(v + bv[ni]);
;           const int tok = m0 + row;
;           p.u()[(size_t)tok * NU + n0 + col] = hv;
	v_add_f32_e32 v124, v246, v124
	v_cvt_f16_f32_e32 v124, v124
	v_add_f32_e32 v125, v246, v125
	v_cvt_f16_f32_e32 v125, v125
	v_add_f32_e32 v126, v246, v126
	v_cvt_f16_f32_e32 v126, v126
	v_add_f32_e32 v127, v246, v127
	v_cvt_f16_f32_e32 v127, v127
	v_add_f32_e32 v128, v246, v128
	v_cvt_f16_f32_e32 v128, v128
	v_add_f32_e32 v129, v246, v129
	v_cvt_f16_f32_e32 v129, v129
	v_add_f32_e32 v98, v187, v98
	v_cvt_f16_f32_e32 v98, v98
	v_add_f32_e32 v99, v187, v99
	v_cvt_f16_f32_e32 v99, v99
	v_add_f32_e32 v100, v187, v100
	v_cvt_f16_f32_e32 v100, v100
	v_add_f32_e32 v101, v187, v101
	v_cvt_f16_f32_e32 v101, v101
	v_add_f32_e32 v102, v187, v102
	v_cvt_f16_f32_e32 v102, v102
	v_add_f32_e32 v103, v187, v103
	v_cvt_f16_f32_e32 v103, v103
	v_add_f32_e32 v104, v187, v104
	v_cvt_f16_f32_e32 v104, v104
	v_add_f32_e32 v105, v187, v105
	v_cvt_f16_f32_e32 v105, v105
	v_add_f32_e32 v106, v187, v106
	v_cvt_f16_f32_e32 v106, v106
	v_add_f32_e32 v107, v187, v107
	v_cvt_f16_f32_e32 v107, v107
	v_add_f32_e32 v108, v187, v108
	v_cvt_f16_f32_e32 v108, v108
	v_add_f32_e32 v109, v187, v109
	v_cvt_f16_f32_e32 v109, v109
	v_add_f32_e32 v110, v187, v110
	v_cvt_f16_f32_e32 v110, v110
	v_add_f32_e32 v111, v187, v111
	v_cvt_f16_f32_e32 v111, v111
	v_add_f32_e32 v112, v187, v112
	v_cvt_f16_f32_e32 v112, v112
	v_add_f32_e32 v113, v187, v113
	v_cvt_f16_f32_e32 v113, v113
	v_add_f32_e32 v82, v246, v82
	v_cvt_f16_f32_e32 v82, v82
	v_add_f32_e32 v83, v246, v83
	v_cvt_f16_f32_e32 v83, v83
	v_add_f32_e32 v84, v246, v84
	v_cvt_f16_f32_e32 v84, v84
	v_add_f32_e32 v85, v246, v85
	v_cvt_f16_f32_e32 v85, v85
	v_add_f32_e32 v86, v246, v86
	v_cvt_f16_f32_e32 v86, v86
	v_add_f32_e32 v87, v246, v87
	v_cvt_f16_f32_e32 v87, v87
	v_add_f32_e32 v88, v246, v88
	v_cvt_f16_f32_e32 v88, v88
	v_add_f32_e32 v89, v246, v89
	v_cvt_f16_f32_e32 v89, v89
	v_add_f32_e32 v90, v246, v90
	v_cvt_f16_f32_e32 v90, v90
	v_add_f32_e32 v91, v246, v91
	v_cvt_f16_f32_e32 v91, v91
	v_add_f32_e32 v92, v246, v92
	v_cvt_f16_f32_e32 v92, v92
	v_add_f32_e32 v93, v246, v93
	v_cvt_f16_f32_e32 v93, v93
	v_add_f32_e32 v94, v246, v94
	v_cvt_f16_f32_e32 v94, v94
	v_add_f32_e32 v95, v246, v95
	v_cvt_f16_f32_e32 v95, v95
	v_add_f32_e32 v96, v246, v96
	v_cvt_f16_f32_e32 v96, v96
	v_add_f32_e32 v97, v246, v97
	v_cvt_f16_f32_e32 v97, v97
	v_add_f32_e32 v66, v187, v66
	v_cvt_f16_f32_e32 v66, v66
	v_add_f32_e32 v67, v187, v67
	v_cvt_f16_f32_e32 v67, v67
	v_add_f32_e32 v68, v187, v68
	v_cvt_f16_f32_e32 v68, v68
	v_add_f32_e32 v69, v187, v69
	v_cvt_f16_f32_e32 v69, v69
	v_add_f32_e32 v70, v187, v70
	v_cvt_f16_f32_e32 v70, v70
	v_add_f32_e32 v71, v187, v71
	v_cvt_f16_f32_e32 v71, v71
	v_add_f32_e32 v72, v187, v72
	v_cvt_f16_f32_e32 v72, v72
	v_add_f32_e32 v73, v187, v73
	v_cvt_f16_f32_e32 v73, v73
	v_add_f32_e32 v74, v187, v74
	v_cvt_f16_f32_e32 v74, v74
	v_add_f32_e32 v75, v187, v75
	v_cvt_f16_f32_e32 v75, v75
	v_add_f32_e32 v76, v187, v76
	v_cvt_f16_f32_e32 v76, v76
	v_add_f32_e32 v77, v187, v77
	v_cvt_f16_f32_e32 v77, v77
	v_add_f32_e32 v78, v187, v78
	v_cvt_f16_f32_e32 v78, v78
	v_add_f32_e32 v79, v187, v79
	v_cvt_f16_f32_e32 v79, v79
	v_add_f32_e32 v80, v187, v80
	v_cvt_f16_f32_e32 v80, v80
	v_add_f32_e32 v81, v187, v81
	v_cvt_f16_f32_e32 v81, v81
	v_add_f32_e32 v50, v246, v50
	v_cvt_f16_f32_e32 v50, v50
	v_add_f32_e32 v51, v246, v51
	v_cvt_f16_f32_e32 v51, v51
	v_add_f32_e32 v52, v246, v52
	v_cvt_f16_f32_e32 v52, v52
	v_add_f32_e32 v53, v246, v53
	v_cvt_f16_f32_e32 v53, v53
	v_add_f32_e32 v54, v246, v54
	v_cvt_f16_f32_e32 v54, v54
	v_add_f32_e32 v55, v246, v55
	v_cvt_f16_f32_e32 v55, v55
	v_add_f32_e32 v56, v246, v56
	v_cvt_f16_f32_e32 v56, v56
	v_add_f32_e32 v57, v246, v57
	v_cvt_f16_f32_e32 v57, v57
	v_add_f32_e32 v58, v246, v58
	v_cvt_f16_f32_e32 v58, v58
	v_add_f32_e32 v59, v246, v59
	v_cvt_f16_f32_e32 v59, v59
	v_add_f32_e32 v60, v246, v60
	v_cvt_f16_f32_e32 v60, v60
	v_add_f32_e32 v61, v246, v61
	v_cvt_f16_f32_e32 v61, v61
	v_add_f32_e32 v62, v246, v62
	v_cvt_f16_f32_e32 v62, v62
	v_add_f32_e32 v63, v246, v63
	v_cvt_f16_f32_e32 v63, v63
	v_add_f32_e32 v64, v246, v64
	v_cvt_f16_f32_e32 v64, v64
	v_add_f32_e32 v65, v246, v65
	v_cvt_f16_f32_e32 v65, v65
	v_add_f32_e32 v34, v187, v34
	v_cvt_f16_f32_e32 v34, v34
	v_add_f32_e32 v35, v187, v35
	v_cvt_f16_f32_e32 v35, v35
	v_add_f32_e32 v36, v187, v36
	v_cvt_f16_f32_e32 v36, v36
	v_add_f32_e32 v37, v187, v37
	v_cvt_f16_f32_e32 v37, v37
	v_add_f32_e32 v38, v187, v38
	v_cvt_f16_f32_e32 v38, v38
	v_add_f32_e32 v39, v187, v39
	v_cvt_f16_f32_e32 v39, v39
	v_add_f32_e32 v40, v187, v40
	v_cvt_f16_f32_e32 v40, v40
	v_add_f32_e32 v41, v187, v41
	v_cvt_f16_f32_e32 v41, v41
	v_add_f32_e32 v42, v187, v42
	v_cvt_f16_f32_e32 v42, v42
	v_add_f32_e32 v43, v187, v43
	v_cvt_f16_f32_e32 v43, v43
	v_add_f32_e32 v44, v187, v44
	v_cvt_f16_f32_e32 v44, v44
	v_add_f32_e32 v45, v187, v45
	v_cvt_f16_f32_e32 v45, v45
	v_add_f32_e32 v46, v187, v46
	v_cvt_f16_f32_e32 v46, v46
	v_add_f32_e32 v47, v187, v47
	v_cvt_f16_f32_e32 v47, v47
	v_add_f32_e32 v48, v187, v48
	v_cvt_f16_f32_e32 v48, v48
	v_add_f32_e32 v49, v187, v49
	v_cvt_f16_f32_e32 v49, v49
	v_add_f32_e32 v18, v246, v18
	v_cvt_f16_f32_e32 v18, v18
	v_add_f32_e32 v19, v246, v19
	v_cvt_f16_f32_e32 v19, v19
	v_add_f32_e32 v20, v246, v20
	v_cvt_f16_f32_e32 v20, v20
	v_add_f32_e32 v21, v246, v21
	v_cvt_f16_f32_e32 v21, v21
	v_add_f32_e32 v22, v246, v22
	v_cvt_f16_f32_e32 v22, v22
	v_add_f32_e32 v23, v246, v23
	v_cvt_f16_f32_e32 v23, v23
	v_add_f32_e32 v24, v246, v24
	v_cvt_f16_f32_e32 v24, v24
	v_add_f32_e32 v25, v246, v25
	v_cvt_f16_f32_e32 v25, v25
	v_add_f32_e32 v26, v246, v26
	v_cvt_f16_f32_e32 v26, v26
	v_add_f32_e32 v27, v246, v27
	v_cvt_f16_f32_e32 v27, v27
;   __device__ __forceinline__ half_t* u() const { return (half_t*)(ws() + OFF_u); }
; __device__ __forceinline__ void phase_inproj(const KP& p, int l, char* smem, int* q, int xcc) {
;     ...
;         [&](int mi, int ni, int r, int row, int col, float v) {
;           const half_t hv = (half_t)(v + bv[ni]);
;           const int tok = m0 + row;
;           p.u()[(size_t)tok * NU + n0 + col] = hv;
	v_add_f32_e32 v28, v246, v28
	v_cvt_f16_f32_e32 v28, v28
	v_add_f32_e32 v29, v246, v29
	v_cvt_f16_f32_e32 v29, v29
	v_add_f32_e32 v30, v246, v30
	v_cvt_f16_f32_e32 v30, v30
	v_add_f32_e32 v31, v246, v31
	v_cvt_f16_f32_e32 v31, v31
	v_add_f32_e32 v32, v246, v32
	v_cvt_f16_f32_e32 v32, v32
	v_add_f32_e32 v33, v246, v33
	v_cvt_f16_f32_e32 v33, v33
	v_add_f32_e32 v2, v187, v2
	v_cvt_f16_f32_e32 v2, v2
	v_add_f32_e32 v3, v187, v3
	v_cvt_f16_f32_e32 v3, v3
	v_add_f32_e32 v4, v187, v4
	v_cvt_f16_f32_e32 v4, v4
	v_add_f32_e32 v5, v187, v5
	v_cvt_f16_f32_e32 v5, v5
	v_add_f32_e32 v6, v187, v6
	v_cvt_f16_f32_e32 v6, v6
	v_add_f32_e32 v7, v187, v7
	v_cvt_f16_f32_e32 v7, v7
	v_add_f32_e32 v8, v187, v8
	v_cvt_f16_f32_e32 v8, v8
	v_add_f32_e32 v9, v187, v9
	v_cvt_f16_f32_e32 v9, v9
	v_add_f32_e32 v10, v187, v10
	v_cvt_f16_f32_e32 v10, v10
	v_add_f32_e32 v11, v187, v11
	v_cvt_f16_f32_e32 v11, v11
	v_add_f32_e32 v12, v187, v12
	v_cvt_f16_f32_e32 v12, v12
	v_add_f32_e32 v13, v187, v13
	v_cvt_f16_f32_e32 v13, v13
	v_add_f32_e32 v14, v187, v14
	v_cvt_f16_f32_e32 v14, v14
	v_add_f32_e32 v15, v187, v15
	v_cvt_f16_f32_e32 v15, v15
	v_add_f32_e32 v16, v187, v16
	v_cvt_f16_f32_e32 v16, v16
	v_add_f32_e32 v17, v187, v17
	v_cvt_f16_f32_e32 v17, v17
	s_add_u32 s2, s18, 0x0
	s_addc_u32 s3, s19, 0
	global_store_short v132, v114, s[2:3]
	global_store_short v132, v98, s[2:3] offset:64
	s_add_u32 s2, s18, 0x3a00
	s_addc_u32 s3, s19, 0
	global_store_short v132, v115, s[2:3]
	global_store_short v132, v99, s[2:3] offset:64
	s_add_u32 s2, s18, 0x7400
	s_addc_u32 s3, s19, 0
	global_store_short v132, v116, s[2:3]
	global_store_short v132, v100, s[2:3] offset:64
	s_add_u32 s2, s18, 0xae00
	s_addc_u32 s3, s19, 0
	global_store_short v132, v117, s[2:3]
	global_store_short v132, v101, s[2:3] offset:64
	s_add_u32 s2, s18, 0x1d000
	s_addc_u32 s3, s19, 0
	global_store_short v132, v118, s[2:3]
	global_store_short v132, v102, s[2:3] offset:64
	s_add_u32 s2, s18, 0x20a00
	s_addc_u32 s3, s19, 0
	global_store_short v132, v119, s[2:3]
	global_store_short v132, v103, s[2:3] offset:64
	s_add_u32 s2, s18, 0x24400
	s_addc_u32 s3, s19, 0
	global_store_short v132, v120, s[2:3]
	global_store_short v132, v104, s[2:3] offset:64
	s_add_u32 s2, s18, 0x27e00
	s_addc_u32 s3, s19, 0
	global_store_short v132, v121, s[2:3]
	global_store_short v132, v105, s[2:3] offset:64
	s_add_u32 s2, s18, 0x3a000
	s_addc_u32 s3, s19, 0
	global_store_short v132, v122, s[2:3]
	global_store_short v132, v106, s[2:3] offset:64
	s_add_u32 s2, s18, 0x3da00
	s_addc_u32 s3, s19, 0
	global_store_short v132, v123, s[2:3]
	global_store_short v132, v107, s[2:3] offset:64
	s_add_u32 s2, s18, 0x41400
	s_addc_u32 s3, s19, 0
	global_store_short v132, v124, s[2:3]
	global_store_short v132, v108, s[2:3] offset:64
	s_add_u32 s2, s18, 0x44e00
	s_addc_u32 s3, s19, 0
	global_store_short v132, v125, s[2:3]
	global_store_short v132, v109, s[2:3] offset:64
	s_add_u32 s2, s18, 0x57000
	s_addc_u32 s3, s19, 0
	global_store_short v132, v126, s[2:3]
	global_store_short v132, v110, s[2:3] offset:64
	s_add_u32 s2, s18, 0x5aa00
	s_addc_u32 s3, s19, 0
	global_store_short v132, v127, s[2:3]
	global_store_short v132, v111, s[2:3] offset:64
	s_add_u32 s2, s18, 0x5e400
	s_addc_u32 s3, s19, 0
	global_store_short v132, v128, s[2:3]
	global_store_short v132, v112, s[2:3] offset:64
	s_add_u32 s2, s18, 0x61e00
	s_addc_u32 s3, s19, 0
	global_store_short v132, v129, s[2:3]
	global_store_short v132, v113, s[2:3] offset:64
	s_add_u32 s2, s18, 0x74000
	s_addc_u32 s3, s19, 0
	global_store_short v132, v82, s[2:3]
	global_store_short v132, v66, s[2:3] offset:64
	s_add_u32 s2, s18, 0x77a00
	s_addc_u32 s3, s19, 0
	global_store_short v132, v83, s[2:3]
	global_store_short v132, v67, s[2:3] offset:64
	s_add_u32 s2, s18, 0x7b400
	s_addc_u32 s3, s19, 0
	global_store_short v132, v84, s[2:3]
	global_store_short v132, v68, s[2:3] offset:64
	s_add_u32 s2, s18, 0x7ee00
	s_addc_u32 s3, s19, 0
	global_store_short v132, v85, s[2:3]
	global_store_short v132, v69, s[2:3] offset:64
	s_add_u32 s2, s18, 0x91000
	s_addc_u32 s3, s19, 0
	global_store_short v132, v86, s[2:3]
	global_store_short v132, v70, s[2:3] offset:64
	s_add_u32 s2, s18, 0x94a00
	s_addc_u32 s3, s19, 0
	global_store_short v132, v87, s[2:3]
	global_store_short v132, v71, s[2:3] offset:64
	s_add_u32 s2, s18, 0x98400
	s_addc_u32 s3, s19, 0
	global_store_short v132, v88, s[2:3]
	global_store_short v132, v72, s[2:3] offset:64
	s_add_u32 s2, s18, 0x9be00
	s_addc_u32 s3, s19, 0
	global_store_short v132, v89, s[2:3]
	global_store_short v132, v73, s[2:3] offset:64
	s_add_u32 s2, s18, 0xae000
	s_addc_u32 s3, s19, 0
	global_store_short v132, v90, s[2:3]
	global_store_short v132, v74, s[2:3] offset:64
	s_add_u32 s2, s18, 0xb1a00
	s_addc_u32 s3, s19, 0
	global_store_short v132, v91, s[2:3]
	global_store_short v132, v75, s[2:3] offset:64
	s_add_u32 s2, s18, 0xb5400
	s_addc_u32 s3, s19, 0
	global_store_short v132, v92, s[2:3]
	global_store_short v132, v76, s[2:3] offset:64
	s_add_u32 s2, s18, 0xb8e00
	s_addc_u32 s3, s19, 0
	global_store_short v132, v93, s[2:3]
	global_store_short v132, v77, s[2:3] offset:64
	s_add_u32 s2, s18, 0xcb000
	s_addc_u32 s3, s19, 0
	global_store_short v132, v94, s[2:3]
	global_store_short v132, v78, s[2:3] offset:64
	s_add_u32 s2, s18, 0xcea00
	s_addc_u32 s3, s19, 0
	global_store_short v132, v95, s[2:3]
	global_store_short v132, v79, s[2:3] offset:64
	s_add_u32 s2, s18, 0xd2400
	s_addc_u32 s3, s19, 0
	global_store_short v132, v96, s[2:3]
	global_store_short v132, v80, s[2:3] offset:64
	s_add_u32 s2, s18, 0xd5e00
	s_addc_u32 s3, s19, 0
	global_store_short v132, v97, s[2:3]
	global_store_short v132, v81, s[2:3] offset:64
;   __device__ __forceinline__ half_t* u() const { return (half_t*)(ws() + OFF_u); }
; __device__ __forceinline__ void phase_inproj(const KP& p, int l, char* smem, int* q, int xcc) {
;     ...
;         [&](int mi, int ni, int r, int row, int col, float v) {
;           const half_t hv = (half_t)(v + bv[ni]);
;           const int tok = m0 + row;
;           p.u()[(size_t)tok * NU + n0 + col] = hv;
;           if (vT) {
	s_add_u32 s2, s18, 0xe8000
	s_addc_u32 s3, s19, 0
	global_store_short v132, v50, s[2:3]
	global_store_short v132, v34, s[2:3] offset:64
	s_add_u32 s2, s18, 0xeba00
	s_addc_u32 s3, s19, 0
	global_store_short v132, v51, s[2:3]
	global_store_short v132, v35, s[2:3] offset:64
	s_add_u32 s2, s18, 0xef400
	s_addc_u32 s3, s19, 0
	global_store_short v132, v52, s[2:3]
	global_store_short v132, v36, s[2:3] offset:64
	s_add_u32 s2, s18, 0xf2e00
	s_addc_u32 s3, s19, 0
	global_store_short v132, v53, s[2:3]
	global_store_short v132, v37, s[2:3] offset:64
	s_add_u32 s2, s18, 0x105000
	s_addc_u32 s3, s19, 0
	global_store_short v132, v54, s[2:3]
	global_store_short v132, v38, s[2:3] offset:64
	s_add_u32 s2, s18, 0x108a00
	s_addc_u32 s3, s19, 0
	global_store_short v132, v55, s[2:3]
	global_store_short v132, v39, s[2:3] offset:64
	s_add_u32 s2, s18, 0x10c400
	s_addc_u32 s3, s19, 0
	global_store_short v132, v56, s[2:3]
	global_store_short v132, v40, s[2:3] offset:64
	s_add_u32 s2, s18, 0x10fe00
	s_addc_u32 s3, s19, 0
	global_store_short v132, v57, s[2:3]
	global_store_short v132, v41, s[2:3] offset:64
	s_add_u32 s2, s18, 0x122000
	s_addc_u32 s3, s19, 0
	global_store_short v132, v58, s[2:3]
	global_store_short v132, v42, s[2:3] offset:64
	s_add_u32 s2, s18, 0x125a00
	s_addc_u32 s3, s19, 0
	global_store_short v132, v59, s[2:3]
	global_store_short v132, v43, s[2:3] offset:64
	s_add_u32 s2, s18, 0x129400
	s_addc_u32 s3, s19, 0
	global_store_short v132, v60, s[2:3]
	global_store_short v132, v44, s[2:3] offset:64
	s_add_u32 s2, s18, 0x12ce00
	s_addc_u32 s3, s19, 0
	global_store_short v132, v61, s[2:3]
	global_store_short v132, v45, s[2:3] offset:64
	s_add_u32 s2, s18, 0x13f000
	s_addc_u32 s3, s19, 0
	global_store_short v132, v62, s[2:3]
	global_store_short v132, v46, s[2:3] offset:64
	s_add_u32 s2, s18, 0x142a00
	s_addc_u32 s3, s19, 0
	global_store_short v132, v63, s[2:3]
	global_store_short v132, v47, s[2:3] offset:64
	s_add_u32 s2, s18, 0x146400
	s_addc_u32 s3, s19, 0
	global_store_short v132, v64, s[2:3]
	global_store_short v132, v48, s[2:3] offset:64
	s_add_u32 s2, s18, 0x149e00
	s_addc_u32 s3, s19, 0
	global_store_short v132, v65, s[2:3]
	global_store_short v132, v49, s[2:3] offset:64
	s_add_u32 s2, s18, 0x15c000
	s_addc_u32 s3, s19, 0
	global_store_short v132, v18, s[2:3]
	global_store_short v132, v2, s[2:3] offset:64
	s_add_u32 s2, s18, 0x15fa00
	s_addc_u32 s3, s19, 0
	global_store_short v132, v19, s[2:3]
	global_store_short v132, v3, s[2:3] offset:64
	s_add_u32 s2, s18, 0x163400
	s_addc_u32 s3, s19, 0
	global_store_short v132, v20, s[2:3]
	global_store_short v132, v4, s[2:3] offset:64
	s_add_u32 s2, s18, 0x166e00
	s_addc_u32 s3, s19, 0
	global_store_short v132, v21, s[2:3]
	global_store_short v132, v5, s[2:3] offset:64
	s_add_u32 s2, s18, 0x179000
	s_addc_u32 s3, s19, 0
	global_store_short v132, v22, s[2:3]
	global_store_short v132, v6, s[2:3] offset:64
	s_add_u32 s2, s18, 0x17ca00
	s_addc_u32 s3, s19, 0
	global_store_short v132, v23, s[2:3]
	global_store_short v132, v7, s[2:3] offset:64
	s_add_u32 s2, s18, 0x180400
	s_addc_u32 s3, s19, 0
	global_store_short v132, v24, s[2:3]
	global_store_short v132, v8, s[2:3] offset:64
	s_add_u32 s2, s18, 0x183e00
	s_addc_u32 s3, s19, 0
	global_store_short v132, v25, s[2:3]
	global_store_short v132, v9, s[2:3] offset:64
	s_add_u32 s2, s18, 0x196000
	s_addc_u32 s3, s19, 0
	global_store_short v132, v26, s[2:3]
	global_store_short v132, v10, s[2:3] offset:64
	s_add_u32 s2, s18, 0x199a00
	s_addc_u32 s3, s19, 0
	global_store_short v132, v27, s[2:3]
	global_store_short v132, v11, s[2:3] offset:64
	s_add_u32 s2, s18, 0x19d400
	s_addc_u32 s3, s19, 0
	global_store_short v132, v28, s[2:3]
	global_store_short v132, v12, s[2:3] offset:64
	s_add_u32 s2, s18, 0x1a0e00
	s_addc_u32 s3, s19, 0
	global_store_short v132, v29, s[2:3]
	global_store_short v132, v13, s[2:3] offset:64
	s_add_u32 s2, s18, 0x1b3000
	s_addc_u32 s3, s19, 0
	global_store_short v132, v30, s[2:3]
	global_store_short v132, v14, s[2:3] offset:64
	s_add_u32 s2, s18, 0x1b6a00
	s_addc_u32 s3, s19, 0
	global_store_short v132, v31, s[2:3]
	global_store_short v132, v15, s[2:3] offset:64
	s_add_u32 s2, s18, 0x1ba400
	s_addc_u32 s3, s19, 0
	global_store_short v132, v32, s[2:3]
	global_store_short v132, v16, s[2:3] offset:64
	s_add_u32 s2, s18, 0x1bde00
	s_addc_u32 s3, s19, 0
	global_store_short v132, v33, s[2:3]
	global_store_short v132, v17, s[2:3] offset:64
	s_cmp_lg_u64 s[40:41], 0
	s_cbranch_scc0 .Lip_novt
; __device__ __forceinline__ void phase_inproj(const KP& p, int l, char* smem, int* q, int xcc) {
;     ...
;           if (vT) {
;             const int b = tok >> 13, t = tok & 8191;
;             vT[((size_t)(b * 2 + (col >> 6)) * 64 + (col & 63)) * SEQ + t] = hv;
;           }
	s_lshr_b32 s2, s14, 13
	s_lshl_b32 s2, s2, 21
	s_and_b32 s3, s14, 0x1fff
	s_lshl_b32 s3, s3, 1
	s_add_u32 s2, s2, s3
	s_add_u32 s40, s40, s2
	s_addc_u32 s41, s41, 0
	v_lshlrev_b32_e32 v135, 14, v134
	v_lshl_add_u32 v135, v130, 3, v135
	v_pack_b32_f16 v136, v114, v115
	v_pack_b32_f16 v137, v116, v117
	s_add_u32 s2, s40, 0x0
	s_addc_u32 s3, s41, 0
	global_store_dwordx2 v135, v[136:137], s[2:3]
	v_pack_b32_f16 v138, v118, v119
	v_pack_b32_f16 v139, v120, v121
	s_add_u32 s2, s40, 0x10
	s_addc_u32 s3, s41, 0
	global_store_dwordx2 v135, v[138:139], s[2:3]
	v_pack_b32_f16 v140, v122, v123
	v_pack_b32_f16 v141, v124, v125
	s_add_u32 s2, s40, 0x20
	s_addc_u32 s3, s41, 0
	global_store_dwordx2 v135, v[140:141], s[2:3]
	v_pack_b32_f16 v142, v126, v127
	v_pack_b32_f16 v143, v128, v129
	s_add_u32 s2, s40, 0x30
	s_addc_u32 s3, s41, 0
	global_store_dwordx2 v135, v[142:143], s[2:3]
	v_pack_b32_f16 v136, v98, v99
	v_pack_b32_f16 v137, v100, v101
	s_add_u32 s2, s40, 0x80000
	s_addc_u32 s3, s41, 0
	global_store_dwordx2 v135, v[136:137], s[2:3]
	v_pack_b32_f16 v138, v102, v103
	v_pack_b32_f16 v139, v104, v105
	s_add_u32 s2, s40, 0x80010
	s_addc_u32 s3, s41, 0
	global_store_dwordx2 v135, v[138:139], s[2:3]
	v_pack_b32_f16 v140, v106, v107
	v_pack_b32_f16 v141, v108, v109
	s_add_u32 s2, s40, 0x80020
	s_addc_u32 s3, s41, 0
	global_store_dwordx2 v135, v[140:141], s[2:3]
	v_pack_b32_f16 v142, v110, v111
	v_pack_b32_f16 v143, v112, v113
	s_add_u32 s2, s40, 0x80030
	s_addc_u32 s3, s41, 0
	global_store_dwordx2 v135, v[142:143], s[2:3]
	v_pack_b32_f16 v136, v82, v83
	v_pack_b32_f16 v137, v84, v85
	s_add_u32 s2, s40, 0x40
	s_addc_u32 s3, s41, 0
	global_store_dwordx2 v135, v[136:137], s[2:3]
	v_pack_b32_f16 v138, v86, v87
	v_pack_b32_f16 v139, v88, v89
	s_add_u32 s2, s40, 0x50
	s_addc_u32 s3, s41, 0
	global_store_dwordx2 v135, v[138:139], s[2:3]
	v_pack_b32_f16 v140, v90, v91
	v_pack_b32_f16 v141, v92, v93
	s_add_u32 s2, s40, 0x60
	s_addc_u32 s3, s41, 0
	global_store_dwordx2 v135, v[140:141], s[2:3]
	v_pack_b32_f16 v142, v94, v95
	v_pack_b32_f16 v143, v96, v97
	s_add_u32 s2, s40, 0x70
	s_addc_u32 s3, s41, 0
	global_store_dwordx2 v135, v[142:143], s[2:3]
	v_pack_b32_f16 v136, v66, v67
	v_pack_b32_f16 v137, v68, v69
	s_add_u32 s2, s40, 0x80040
	s_addc_u32 s3, s41, 0
	global_store_dwordx2 v135, v[136:137], s[2:3]
	v_pack_b32_f16 v138, v70, v71
	v_pack_b32_f16 v139, v72, v73
	s_add_u32 s2, s40, 0x80050
	s_addc_u32 s3, s41, 0
	global_store_dwordx2 v135, v[138:139], s[2:3]
	v_pack_b32_f16 v140, v74, v75
	v_pack_b32_f16 v141, v76, v77
	s_add_u32 s2, s40, 0x80060
	s_addc_u32 s3, s41, 0
	global_store_dwordx2 v135, v[140:141], s[2:3]
	v_pack_b32_f16 v142, v78, v79
	v_pack_b32_f16 v143, v80, v81
	s_add_u32 s2, s40, 0x80070
	s_addc_u32 s3, s41, 0
	global_store_dwordx2 v135, v[142:143], s[2:3]
	v_pack_b32_f16 v136, v50, v51
	v_pack_b32_f16 v137, v52, v53
	s_add_u32 s2, s40, 0x80
	s_addc_u32 s3, s41, 0
	global_store_dwordx2 v135, v[136:137], s[2:3]
	v_pack_b32_f16 v138, v54, v55
	v_pack_b32_f16 v139, v56, v57
	s_add_u32 s2, s40, 0x90
	s_addc_u32 s3, s41, 0
	global_store_dwordx2 v135, v[138:139], s[2:3]
	v_pack_b32_f16 v140, v58, v59
	v_pack_b32_f16 v141, v60, v61
	s_add_u32 s2, s40, 0xa0
	s_addc_u32 s3, s41, 0
	global_store_dwordx2 v135, v[140:141], s[2:3]
	v_pack_b32_f16 v142, v62, v63
	v_pack_b32_f16 v143, v64, v65
	s_add_u32 s2, s40, 0xb0
	s_addc_u32 s3, s41, 0
	global_store_dwordx2 v135, v[142:143], s[2:3]
	v_pack_b32_f16 v136, v34, v35
	v_pack_b32_f16 v137, v36, v37
	s_add_u32 s2, s40, 0x80080
	s_addc_u32 s3, s41, 0
	global_store_dwordx2 v135, v[136:137], s[2:3]
	v_pack_b32_f16 v138, v38, v39
	v_pack_b32_f16 v139, v40, v41
	s_add_u32 s2, s40, 0x80090
	s_addc_u32 s3, s41, 0
	global_store_dwordx2 v135, v[138:139], s[2:3]
	v_pack_b32_f16 v140, v42, v43
	v_pack_b32_f16 v141, v44, v45
	s_add_u32 s2, s40, 0x800a0
	s_addc_u32 s3, s41, 0
	global_store_dwordx2 v135, v[140:141], s[2:3]
	v_pack_b32_f16 v142, v46, v47
	v_pack_b32_f16 v143, v48, v49
	s_add_u32 s2, s40, 0x800b0
	s_addc_u32 s3, s41, 0
	global_store_dwordx2 v135, v[142:143], s[2:3]
	v_pack_b32_f16 v136, v18, v19
	v_pack_b32_f16 v137, v20, v21
	s_add_u32 s2, s40, 0xc0
	s_addc_u32 s3, s41, 0
	global_store_dwordx2 v135, v[136:137], s[2:3]
	v_pack_b32_f16 v138, v22, v23
	v_pack_b32_f16 v139, v24, v25
	s_add_u32 s2, s40, 0xd0
	s_addc_u32 s3, s41, 0
	global_store_dwordx2 v135, v[138:139], s[2:3]
	v_pack_b32_f16 v140, v26, v27
	v_pack_b32_f16 v141, v28, v29
	s_add_u32 s2, s40, 0xe0
	s_addc_u32 s3, s41, 0
	global_store_dwordx2 v135, v[140:141], s[2:3]
	v_pack_b32_f16 v142, v30, v31
	v_pack_b32_f16 v143, v32, v33
	s_add_u32 s2, s40, 0xf0
	s_addc_u32 s3, s41, 0
	global_store_dwordx2 v135, v[142:143], s[2:3]
	v_pack_b32_f16 v136, v2, v3
	v_pack_b32_f16 v137, v4, v5
	s_add_u32 s2, s40, 0x800c0
	s_addc_u32 s3, s41, 0
	global_store_dwordx2 v135, v[136:137], s[2:3]
	v_pack_b32_f16 v138, v6, v7
	v_pack_b32_f16 v139, v8, v9
	s_add_u32 s2, s40, 0x800d0
	s_addc_u32 s3, s41, 0
	global_store_dwordx2 v135, v[138:139], s[2:3]
	v_pack_b32_f16 v140, v10, v11
	v_pack_b32_f16 v141, v12, v13
	s_add_u32 s2, s40, 0x800e0
	s_addc_u32 s3, s41, 0
	global_store_dwordx2 v135, v[140:141], s[2:3]
	v_pack_b32_f16 v142, v14, v15
	v_pack_b32_f16 v143, v16, v17
	s_add_u32 s2, s40, 0x800f0
	s_addc_u32 s3, s41, 0
	global_store_dwordx2 v135, v[142:143], s[2:3]
